# scan consumer waves at raised priority during the chunk (on top of y-FMA)
# baseline (speedup 1.0000x reference)
; DI void scan_item(const __attribute__((address_space(4))) Args& a, LAS unsigned char* lds, int ws_, bool is_prompt, int seq, int h, int half, bool dry = false) {
;     ...
;     auto consume = [&](int bsel) {
;         const LAS unsigned char* B = lds + bsel * SC_BUF;
;         const LAS float* opb = (const LAS float*)B + c0;
;         const LAS float* vvb = (const LAS float*)(B + SC_OPS) + i0;
;         const LAS float* scb = (const LAS float*)(B + SC_OPS + SC_VV);
;         LAS float* ybb = cg8 == 0 ? (LAS float*)(B + SC_OPS + SC_VV + SC_SC) + (i0 & 31) : (LAS float*)(lds + 2 * SC_BUF) + (tid & 255);
;         f32x4 n[10]; float nv; f32x2 nbk;
;     ...
;         SC_LOAD(0)
; #pragma unroll 4
;         for (int t = 0; t < SC_CH; ++t) {
;             f32x4 c[10];
; #pragma unroll
;             for (int q = 0; q < 10; ++q) c[q] = n[q];
;             const float v0 = nv; const f32x2 bk = nbk;
;             SC_LOAD(t + 1)
;             __builtin_amdgcn_sched_barrier(0);
;             f32x2 aA = sp[0] * c[0].xy, aY = sp[0] * c[2].xy;
;             aA = sp[1] * c[0].zw + aA; aY = sp[1] * c[2].zw + aY;
;             aA = sp[2] * c[1].xy + aA; aY = sp[2] * c[3].xy + aY;
;             aA = sp[3] * c[1].zw + aA; aY = sp[3] * c[3].zw + aY;
;             float da = aA.x + aA.y, dy = aY.x + aY.y;
;             asm("s_nop 1\n\t"
;                 "v_add_f32_dpp %0, %0, %0 quad_perm:[1,0,3,2] row_mask:0xf bank_mask:0xf bound_ctrl:1\n\t"
;                 "v_add_f32_dpp %1, %1, %1 quad_perm:[1,0,3,2] row_mask:0xf bank_mask:0xf bound_ctrl:1\n\t"
;                 "s_nop 0\n\t"
;                 "v_add_f32_dpp %0, %0, %0 quad_perm:[2,3,0,1] row_mask:0xf bank_mask:0xf bound_ctrl:1\n\t"
;                 "v_add_f32_dpp %1, %1, %1 quad_perm:[2,3,0,1] row_mask:0xf bank_mask:0xf bound_ctrl:1\n\t"
;                 "s_nop 0\n\t"
;                 "v_add_f32_dpp %0, %0, %0 row_half_mirror row_mask:0xf bank_mask:0xf bound_ctrl:1\n\t"
;                 "v_add_f32_dpp %1, %1, %1 row_half_mirror row_mask:0xf bank_mask:0xf bound_ctrl:1"
;                 : "+v"(da), "+v"(dy));
;             {
;                 f32x2 t0;
;                 t0 = c[8].xy * v0; t0 = c[6].xy * da + t0; sp[0] = sp[0] * c[4].xy + t0;
;                 t0 = c[8].zw * v0; t0 = c[6].zw * da + t0; sp[1] = sp[1] * c[4].zw + t0;
;                 t0 = c[9].xy * v0; t0 = c[7].xy * da + t0; sp[2] = sp[2] * c[5].xy + t0;
.LBB0_1535:
	s_and_b64 vcc, exec, s[74:75]
	s_cbranch_vccz .LBB0_1523
	s_setprio 3
	s_bitcmp1_b32 s24, 0
	s_cselect_b32 s34, 0x6900, 0
	s_add_i32 s35, s34, 0
	s_waitcnt vmcnt(0)
	v_lshl_add_u32 v120, v110, 2, s35
	v_lshl_add_u32 v96, v111, 2, s35
	v_lshl_add_u32 v136, v115, 2, s35
	v_mov_b32_e32 v121, s35
	v_add_u32_e32 v136, 0x6100, v136
	v_cndmask_b32_e64 v95, v116, v136, s[8:9]
	ds_read_b128 v[40:43], v120
	ds_read_b128 v[44:47], v120 offset:16
	ds_read_b128 v[48:51], v120 offset:256
	ds_read_b128 v[52:55], v120 offset:272
	ds_read_b128 v[56:59], v120 offset:512
	ds_read_b128 v[60:63], v120 offset:528
	ds_read_b128 v[64:67], v120 offset:768
	ds_read_b128 v[68:71], v120 offset:784
	ds_read_b128 v[72:75], v120 offset:1024
	ds_read_b128 v[76:79], v120 offset:1040
	ds_read_b32 v94, v96 offset:20480
	ds_read_b64 v[108:109], v121 offset:24576
	ds_read_b128 v[190:193], v120 offset:1280
	ds_read_b128 v[194:197], v120 offset:1296
	ds_read_b128 v[198:201], v120 offset:1536
	ds_read_b128 v[202:205], v120 offset:1552
	ds_read_b128 v[206:209], v120 offset:1792
	ds_read_b128 v[210:213], v120 offset:1808
	ds_read_b128 v[214:217], v120 offset:2048
	ds_read_b128 v[218:221], v120 offset:2064
	ds_read_b128 v[222:225], v120 offset:2304
	ds_read_b128 v[226:229], v120 offset:2320
	ds_read_b32 v230, v96 offset:20736
	ds_read_b64 v[232:233], v121 offset:24592
	s_waitcnt lgkmcnt(12)
	v_pk_mul_f32 v[122:123], v[38:39], v[42:43]
	v_pk_mul_f32 v[124:125], v[38:39], v[50:51]
	v_pk_fma_f32 v[122:123], v[36:37], v[40:41], v[122:123]
	v_pk_fma_f32 v[124:125], v[36:37], v[48:49], v[124:125]
	v_pk_fma_f32 v[122:123], v[32:33], v[44:45], v[122:123]
	v_pk_fma_f32 v[124:125], v[32:33], v[52:53], v[124:125]
	v_pk_fma_f32 v[122:123], v[34:35], v[46:47], v[122:123]
	v_pk_fma_f32 v[124:125], v[34:35], v[54:55], v[124:125]
	v_pk_mul_f32 v[126:127], v[72:73], v[94:95] op_sel_hi:[1,0]
	v_add_f32_e32 v166, v122, v123
	v_add_f32_e32 v168, v124, v125
	v_pk_mul_f32 v[128:129], v[74:75], v[94:95] op_sel_hi:[1,0]
	v_pk_mul_f32 v[130:131], v[76:77], v[94:95] op_sel_hi:[1,0]
	v_add_f32_dpp v166, v166, v166 quad_perm:[1,0,3,2] row_mask:0xf bank_mask:0xf bound_ctrl:1
	v_add_f32_dpp v168, v168, v168 quad_perm:[1,0,3,2] row_mask:0xf bank_mask:0xf bound_ctrl:1
	v_pk_mul_f32 v[132:133], v[78:79], v[94:95] op_sel_hi:[1,0]
	v_pk_fma_f32 v[126:127], v[36:37], v[56:57], v[126:127]
	v_add_f32_dpp v166, v166, v166 quad_perm:[2,3,0,1] row_mask:0xf bank_mask:0xf bound_ctrl:1
	v_add_f32_dpp v168, v168, v168 quad_perm:[2,3,0,1] row_mask:0xf bank_mask:0xf bound_ctrl:1
	v_pk_fma_f32 v[128:129], v[38:39], v[58:59], v[128:129]
	v_pk_fma_f32 v[130:131], v[32:33], v[60:61], v[130:131]
	v_add_f32_dpp v166, v166, v166 row_half_mirror row_mask:0xf bank_mask:0xf bound_ctrl:1
	v_add_f32_dpp v168, v168, v168 row_half_mirror row_mask:0xf bank_mask:0xf bound_ctrl:1
	v_pk_fma_f32 v[132:133], v[34:35], v[62:63], v[132:133]
	v_fma_f32 v136, v166, v108, v168
	v_pk_fma_f32 v[36:37], v[64:65], v[166:167], v[126:127] op_sel_hi:[1,0,1]
	v_pk_fma_f32 v[38:39], v[66:67], v[166:167], v[128:129] op_sel_hi:[1,0,1]
	v_pk_fma_f32 v[32:33], v[68:69], v[166:167], v[130:131] op_sel_hi:[1,0,1]
	v_pk_fma_f32 v[34:35], v[70:71], v[166:167], v[132:133] op_sel_hi:[1,0,1]
	v_fma_f32 v136, v94, v109, v136
	ds_write_b32 v95, v136
	ds_read_b128 v[40:43], v120 offset:2560
	ds_read_b128 v[44:47], v120 offset:2576
	ds_read_b128 v[48:51], v120 offset:2816
	ds_read_b128 v[52:55], v120 offset:2832
	ds_read_b128 v[56:59], v120 offset:3072
	ds_read_b128 v[60:63], v120 offset:3088
	ds_read_b128 v[64:67], v120 offset:3328
	ds_read_b128 v[68:71], v120 offset:3344
	ds_read_b128 v[72:75], v120 offset:3584
	ds_read_b128 v[76:79], v120 offset:3600
	ds_read_b32 v94, v96 offset:20992
	ds_read_b64 v[108:109], v121 offset:24608
	s_waitcnt lgkmcnt(12)
	v_pk_mul_f32 v[122:123], v[38:39], v[192:193]
	v_pk_mul_f32 v[124:125], v[38:39], v[200:201]
	v_pk_fma_f32 v[122:123], v[36:37], v[190:191], v[122:123]
	v_pk_fma_f32 v[124:125], v[36:37], v[198:199], v[124:125]
	v_pk_fma_f32 v[122:123], v[32:33], v[194:195], v[122:123]
	v_pk_fma_f32 v[124:125], v[32:33], v[202:203], v[124:125]
	v_pk_fma_f32 v[122:123], v[34:35], v[196:197], v[122:123]
	v_pk_fma_f32 v[124:125], v[34:35], v[204:205], v[124:125]
	v_pk_mul_f32 v[126:127], v[222:223], v[230:231] op_sel_hi:[1,0]
	v_add_f32_e32 v166, v122, v123
	v_add_f32_e32 v168, v124, v125
	v_pk_mul_f32 v[128:129], v[224:225], v[230:231] op_sel_hi:[1,0]
	v_pk_mul_f32 v[130:131], v[226:227], v[230:231] op_sel_hi:[1,0]
	v_add_f32_dpp v166, v166, v166 quad_perm:[1,0,3,2] row_mask:0xf bank_mask:0xf bound_ctrl:1
	v_add_f32_dpp v168, v168, v168 quad_perm:[1,0,3,2] row_mask:0xf bank_mask:0xf bound_ctrl:1
	v_pk_mul_f32 v[132:133], v[228:229], v[230:231] op_sel_hi:[1,0]
	v_pk_fma_f32 v[126:127], v[36:37], v[206:207], v[126:127]
	v_add_f32_dpp v166, v166, v166 quad_perm:[2,3,0,1] row_mask:0xf bank_mask:0xf bound_ctrl:1
	v_add_f32_dpp v168, v168, v168 quad_perm:[2,3,0,1] row_mask:0xf bank_mask:0xf bound_ctrl:1
	v_pk_fma_f32 v[128:129], v[38:39], v[208:209], v[128:129]
	v_pk_fma_f32 v[130:131], v[32:33], v[210:211], v[130:131]
	v_add_f32_dpp v166, v166, v166 row_half_mirror row_mask:0xf bank_mask:0xf bound_ctrl:1
	v_add_f32_dpp v168, v168, v168 row_half_mirror row_mask:0xf bank_mask:0xf bound_ctrl:1
	v_pk_fma_f32 v[132:133], v[34:35], v[212:213], v[132:133]
	v_fma_f32 v136, v166, v232, v168
	v_pk_fma_f32 v[36:37], v[214:215], v[166:167], v[126:127] op_sel_hi:[1,0,1]
	v_pk_fma_f32 v[38:39], v[216:217], v[166:167], v[128:129] op_sel_hi:[1,0,1]
	v_pk_fma_f32 v[32:33], v[218:219], v[166:167], v[130:131] op_sel_hi:[1,0,1]
	v_pk_fma_f32 v[34:35], v[220:221], v[166:167], v[132:133] op_sel_hi:[1,0,1]
	v_fma_f32 v136, v230, v233, v136
	ds_write_b32 v95, v136 offset:128
	ds_read_b128 v[190:193], v120 offset:3840
	ds_read_b128 v[194:197], v120 offset:3856
	ds_read_b128 v[198:201], v120 offset:4096
	ds_read_b128 v[202:205], v120 offset:4112
	ds_read_b128 v[206:209], v120 offset:4352
	ds_read_b128 v[210:213], v120 offset:4368
	ds_read_b128 v[214:217], v120 offset:4608
	ds_read_b128 v[218:221], v120 offset:4624
	ds_read_b128 v[222:225], v120 offset:4864
	ds_read_b128 v[226:229], v120 offset:4880
	ds_read_b32 v230, v96 offset:21248
	ds_read_b64 v[232:233], v121 offset:24624
	s_waitcnt lgkmcnt(12)
; #define SC_LOAD(t) { _Pragma("unroll") for (int q = 0; q < 5; ++q) { n[2 * q] = *(const LAS f32x4*)(opb + (t) * 320 + q * 64); n[2 * q + 1] = *(const LAS f32x4*)(opb + (t) * 320 + q * 64 + 4); } \
;                      nv = vvb[(t) * 64]; nbk = *(const LAS f32x2*)(scb + (t) * 4); }
; DI void scan_item(const __attribute__((address_space(4))) Args& a, LAS unsigned char* lds, int ws_, bool is_prompt, int seq, int h, int half, bool dry = false) {
;     ...
;         SC_LOAD(0)
; #pragma unroll 4
;         for (int t = 0; t < SC_CH; ++t) {
;             f32x4 c[10];
; #pragma unroll
;             for (int q = 0; q < 10; ++q) c[q] = n[q];
;             const float v0 = nv; const f32x2 bk = nbk;
;             SC_LOAD(t + 1)
;             __builtin_amdgcn_sched_barrier(0);
;             f32x2 aA = sp[0] * c[0].xy, aY = sp[0] * c[2].xy;
;             aA = sp[1] * c[0].zw + aA; aY = sp[1] * c[2].zw + aY;
;             aA = sp[2] * c[1].xy + aA; aY = sp[2] * c[3].xy + aY;
;             aA = sp[3] * c[1].zw + aA; aY = sp[3] * c[3].zw + aY;
;             float da = aA.x + aA.y, dy = aY.x + aY.y;
;             asm("s_nop 1\n\t"
;                 "v_add_f32_dpp %0, %0, %0 quad_perm:[1,0,3,2] row_mask:0xf bank_mask:0xf bound_ctrl:1\n\t"
;                 "v_add_f32_dpp %1, %1, %1 quad_perm:[1,0,3,2] row_mask:0xf bank_mask:0xf bound_ctrl:1\n\t"
;                 "s_nop 0\n\t"
;                 "v_add_f32_dpp %0, %0, %0 quad_perm:[2,3,0,1] row_mask:0xf bank_mask:0xf bound_ctrl:1\n\t"
;                 "v_add_f32_dpp %1, %1, %1 quad_perm:[2,3,0,1] row_mask:0xf bank_mask:0xf bound_ctrl:1\n\t"
;                 "s_nop 0\n\t"
;                 "v_add_f32_dpp %0, %0, %0 row_half_mirror row_mask:0xf bank_mask:0xf bound_ctrl:1\n\t"
;                 "v_add_f32_dpp %1, %1, %1 row_half_mirror row_mask:0xf bank_mask:0xf bound_ctrl:1"
;                 : "+v"(da), "+v"(dy));
;             {
;                 f32x2 t0;
;                 t0 = c[8].xy * v0; t0 = c[6].xy * da + t0; sp[0] = sp[0] * c[4].xy + t0;
;                 t0 = c[8].zw * v0; t0 = c[6].zw * da + t0; sp[1] = sp[1] * c[4].zw + t0;
;                 t0 = c[9].xy * v0; t0 = c[7].xy * da + t0; sp[2] = sp[2] * c[5].xy + t0;
;                 t0 = c[9].zw * v0; t0 = c[7].zw * da + t0; sp[3] = sp[3] * c[5].zw + t0;
;             }
;             ybb[t * 32] = dy + da * bk.x + v0 * bk.y;
;         }
	v_pk_mul_f32 v[122:123], v[38:39], v[42:43]
	v_pk_mul_f32 v[124:125], v[38:39], v[50:51]
	v_pk_fma_f32 v[122:123], v[36:37], v[40:41], v[122:123]
	v_pk_fma_f32 v[124:125], v[36:37], v[48:49], v[124:125]
	v_pk_fma_f32 v[122:123], v[32:33], v[44:45], v[122:123]
	v_pk_fma_f32 v[124:125], v[32:33], v[52:53], v[124:125]
	v_pk_fma_f32 v[122:123], v[34:35], v[46:47], v[122:123]
	v_pk_fma_f32 v[124:125], v[34:35], v[54:55], v[124:125]
	v_pk_mul_f32 v[126:127], v[72:73], v[94:95] op_sel_hi:[1,0]
	v_add_f32_e32 v166, v122, v123
	v_add_f32_e32 v168, v124, v125
	v_pk_mul_f32 v[128:129], v[74:75], v[94:95] op_sel_hi:[1,0]
	v_pk_mul_f32 v[130:131], v[76:77], v[94:95] op_sel_hi:[1,0]
	v_add_f32_dpp v166, v166, v166 quad_perm:[1,0,3,2] row_mask:0xf bank_mask:0xf bound_ctrl:1
	v_add_f32_dpp v168, v168, v168 quad_perm:[1,0,3,2] row_mask:0xf bank_mask:0xf bound_ctrl:1
	v_pk_mul_f32 v[132:133], v[78:79], v[94:95] op_sel_hi:[1,0]
	v_pk_fma_f32 v[126:127], v[36:37], v[56:57], v[126:127]
	v_add_f32_dpp v166, v166, v166 quad_perm:[2,3,0,1] row_mask:0xf bank_mask:0xf bound_ctrl:1
	v_add_f32_dpp v168, v168, v168 quad_perm:[2,3,0,1] row_mask:0xf bank_mask:0xf bound_ctrl:1
	v_pk_fma_f32 v[128:129], v[38:39], v[58:59], v[128:129]
	v_pk_fma_f32 v[130:131], v[32:33], v[60:61], v[130:131]
	v_add_f32_dpp v166, v166, v166 row_half_mirror row_mask:0xf bank_mask:0xf bound_ctrl:1
	v_add_f32_dpp v168, v168, v168 row_half_mirror row_mask:0xf bank_mask:0xf bound_ctrl:1
	v_pk_fma_f32 v[132:133], v[34:35], v[62:63], v[132:133]
	v_fma_f32 v136, v166, v108, v168
	v_pk_fma_f32 v[36:37], v[64:65], v[166:167], v[126:127] op_sel_hi:[1,0,1]
	v_pk_fma_f32 v[38:39], v[66:67], v[166:167], v[128:129] op_sel_hi:[1,0,1]
	v_pk_fma_f32 v[32:33], v[68:69], v[166:167], v[130:131] op_sel_hi:[1,0,1]
	v_pk_fma_f32 v[34:35], v[70:71], v[166:167], v[132:133] op_sel_hi:[1,0,1]
	v_fma_f32 v136, v94, v109, v136
	ds_write_b32 v95, v136 offset:256
	ds_read_b128 v[40:43], v120 offset:5120
	ds_read_b128 v[44:47], v120 offset:5136
	ds_read_b128 v[48:51], v120 offset:5376
	ds_read_b128 v[52:55], v120 offset:5392
	ds_read_b128 v[56:59], v120 offset:5632
	ds_read_b128 v[60:63], v120 offset:5648
	ds_read_b128 v[64:67], v120 offset:5888
	ds_read_b128 v[68:71], v120 offset:5904
	ds_read_b128 v[72:75], v120 offset:6144
	ds_read_b128 v[76:79], v120 offset:6160
	ds_read_b32 v94, v96 offset:21504
	ds_read_b64 v[108:109], v121 offset:24640
	s_waitcnt lgkmcnt(12)
	v_pk_mul_f32 v[122:123], v[38:39], v[192:193]
	v_pk_mul_f32 v[124:125], v[38:39], v[200:201]
	v_pk_fma_f32 v[122:123], v[36:37], v[190:191], v[122:123]
	v_pk_fma_f32 v[124:125], v[36:37], v[198:199], v[124:125]
	v_pk_fma_f32 v[122:123], v[32:33], v[194:195], v[122:123]
	v_pk_fma_f32 v[124:125], v[32:33], v[202:203], v[124:125]
	v_pk_fma_f32 v[122:123], v[34:35], v[196:197], v[122:123]
	v_pk_fma_f32 v[124:125], v[34:35], v[204:205], v[124:125]
	v_pk_mul_f32 v[126:127], v[222:223], v[230:231] op_sel_hi:[1,0]
	v_add_f32_e32 v166, v122, v123
	v_add_f32_e32 v168, v124, v125
	v_pk_mul_f32 v[128:129], v[224:225], v[230:231] op_sel_hi:[1,0]
	v_pk_mul_f32 v[130:131], v[226:227], v[230:231] op_sel_hi:[1,0]
	v_add_f32_dpp v166, v166, v166 quad_perm:[1,0,3,2] row_mask:0xf bank_mask:0xf bound_ctrl:1
	v_add_f32_dpp v168, v168, v168 quad_perm:[1,0,3,2] row_mask:0xf bank_mask:0xf bound_ctrl:1
	v_pk_mul_f32 v[132:133], v[228:229], v[230:231] op_sel_hi:[1,0]
	v_pk_fma_f32 v[126:127], v[36:37], v[206:207], v[126:127]
	v_add_f32_dpp v166, v166, v166 quad_perm:[2,3,0,1] row_mask:0xf bank_mask:0xf bound_ctrl:1
	v_add_f32_dpp v168, v168, v168 quad_perm:[2,3,0,1] row_mask:0xf bank_mask:0xf bound_ctrl:1
	v_pk_fma_f32 v[128:129], v[38:39], v[208:209], v[128:129]
	v_pk_fma_f32 v[130:131], v[32:33], v[210:211], v[130:131]
	v_add_f32_dpp v166, v166, v166 row_half_mirror row_mask:0xf bank_mask:0xf bound_ctrl:1
	v_add_f32_dpp v168, v168, v168 row_half_mirror row_mask:0xf bank_mask:0xf bound_ctrl:1
	v_pk_fma_f32 v[132:133], v[34:35], v[212:213], v[132:133]
	v_fma_f32 v136, v166, v232, v168
	v_pk_fma_f32 v[36:37], v[214:215], v[166:167], v[126:127] op_sel_hi:[1,0,1]
	v_pk_fma_f32 v[38:39], v[216:217], v[166:167], v[128:129] op_sel_hi:[1,0,1]
	v_pk_fma_f32 v[32:33], v[218:219], v[166:167], v[130:131] op_sel_hi:[1,0,1]
	v_pk_fma_f32 v[34:35], v[220:221], v[166:167], v[132:133] op_sel_hi:[1,0,1]
	v_fma_f32 v136, v230, v233, v136
	ds_write_b32 v95, v136 offset:384
	ds_read_b128 v[190:193], v120 offset:6400
	ds_read_b128 v[194:197], v120 offset:6416
	ds_read_b128 v[198:201], v120 offset:6656
	ds_read_b128 v[202:205], v120 offset:6672
	ds_read_b128 v[206:209], v120 offset:6912
	ds_read_b128 v[210:213], v120 offset:6928
	ds_read_b128 v[214:217], v120 offset:7168
	ds_read_b128 v[218:221], v120 offset:7184
	ds_read_b128 v[222:225], v120 offset:7424
	ds_read_b128 v[226:229], v120 offset:7440
	ds_read_b32 v230, v96 offset:21760
	ds_read_b64 v[232:233], v121 offset:24656
	s_waitcnt lgkmcnt(12)
; #define SC_LOAD(t) { _Pragma("unroll") for (int q = 0; q < 5; ++q) { n[2 * q] = *(const LAS f32x4*)(opb + (t) * 320 + q * 64); n[2 * q + 1] = *(const LAS f32x4*)(opb + (t) * 320 + q * 64 + 4); } \
;                      nv = vvb[(t) * 64]; nbk = *(const LAS f32x2*)(scb + (t) * 4); }
; DI void scan_item(const __attribute__((address_space(4))) Args& a, LAS unsigned char* lds, int ws_, bool is_prompt, int seq, int h, int half, bool dry = false) {
;     ...
;         SC_LOAD(0)
; #pragma unroll 4
;         for (int t = 0; t < SC_CH; ++t) {
;             f32x4 c[10];
; #pragma unroll
;             for (int q = 0; q < 10; ++q) c[q] = n[q];
;             const float v0 = nv; const f32x2 bk = nbk;
;             SC_LOAD(t + 1)
;             __builtin_amdgcn_sched_barrier(0);
;             f32x2 aA = sp[0] * c[0].xy, aY = sp[0] * c[2].xy;
;             aA = sp[1] * c[0].zw + aA; aY = sp[1] * c[2].zw + aY;
;             aA = sp[2] * c[1].xy + aA; aY = sp[2] * c[3].xy + aY;
;             aA = sp[3] * c[1].zw + aA; aY = sp[3] * c[3].zw + aY;
;             float da = aA.x + aA.y, dy = aY.x + aY.y;
;             asm("s_nop 1\n\t"
;                 "v_add_f32_dpp %0, %0, %0 quad_perm:[1,0,3,2] row_mask:0xf bank_mask:0xf bound_ctrl:1\n\t"
;                 "v_add_f32_dpp %1, %1, %1 quad_perm:[1,0,3,2] row_mask:0xf bank_mask:0xf bound_ctrl:1\n\t"
;                 "s_nop 0\n\t"
;                 "v_add_f32_dpp %0, %0, %0 quad_perm:[2,3,0,1] row_mask:0xf bank_mask:0xf bound_ctrl:1\n\t"
;                 "v_add_f32_dpp %1, %1, %1 quad_perm:[2,3,0,1] row_mask:0xf bank_mask:0xf bound_ctrl:1\n\t"
;                 "s_nop 0\n\t"
;                 "v_add_f32_dpp %0, %0, %0 row_half_mirror row_mask:0xf bank_mask:0xf bound_ctrl:1\n\t"
;                 "v_add_f32_dpp %1, %1, %1 row_half_mirror row_mask:0xf bank_mask:0xf bound_ctrl:1"
;                 : "+v"(da), "+v"(dy));
;             {
;                 f32x2 t0;
;                 t0 = c[8].xy * v0; t0 = c[6].xy * da + t0; sp[0] = sp[0] * c[4].xy + t0;
;                 t0 = c[8].zw * v0; t0 = c[6].zw * da + t0; sp[1] = sp[1] * c[4].zw + t0;
;                 t0 = c[9].xy * v0; t0 = c[7].xy * da + t0; sp[2] = sp[2] * c[5].xy + t0;
;                 t0 = c[9].zw * v0; t0 = c[7].zw * da + t0; sp[3] = sp[3] * c[5].zw + t0;
;             }
;             ybb[t * 32] = dy + da * bk.x + v0 * bk.y;
;         }
	v_pk_mul_f32 v[122:123], v[38:39], v[42:43]
	v_pk_mul_f32 v[124:125], v[38:39], v[50:51]
	v_pk_fma_f32 v[122:123], v[36:37], v[40:41], v[122:123]
	v_pk_fma_f32 v[124:125], v[36:37], v[48:49], v[124:125]
	v_pk_fma_f32 v[122:123], v[32:33], v[44:45], v[122:123]
	v_pk_fma_f32 v[124:125], v[32:33], v[52:53], v[124:125]
	v_pk_fma_f32 v[122:123], v[34:35], v[46:47], v[122:123]
	v_pk_fma_f32 v[124:125], v[34:35], v[54:55], v[124:125]
	v_pk_mul_f32 v[126:127], v[72:73], v[94:95] op_sel_hi:[1,0]
	v_add_f32_e32 v166, v122, v123
	v_add_f32_e32 v168, v124, v125
	v_pk_mul_f32 v[128:129], v[74:75], v[94:95] op_sel_hi:[1,0]
	v_pk_mul_f32 v[130:131], v[76:77], v[94:95] op_sel_hi:[1,0]
	v_add_f32_dpp v166, v166, v166 quad_perm:[1,0,3,2] row_mask:0xf bank_mask:0xf bound_ctrl:1
	v_add_f32_dpp v168, v168, v168 quad_perm:[1,0,3,2] row_mask:0xf bank_mask:0xf bound_ctrl:1
	v_pk_mul_f32 v[132:133], v[78:79], v[94:95] op_sel_hi:[1,0]
	v_pk_fma_f32 v[126:127], v[36:37], v[56:57], v[126:127]
	v_add_f32_dpp v166, v166, v166 quad_perm:[2,3,0,1] row_mask:0xf bank_mask:0xf bound_ctrl:1
	v_add_f32_dpp v168, v168, v168 quad_perm:[2,3,0,1] row_mask:0xf bank_mask:0xf bound_ctrl:1
	v_pk_fma_f32 v[128:129], v[38:39], v[58:59], v[128:129]
	v_pk_fma_f32 v[130:131], v[32:33], v[60:61], v[130:131]
	v_add_f32_dpp v166, v166, v166 row_half_mirror row_mask:0xf bank_mask:0xf bound_ctrl:1
	v_add_f32_dpp v168, v168, v168 row_half_mirror row_mask:0xf bank_mask:0xf bound_ctrl:1
	v_pk_fma_f32 v[132:133], v[34:35], v[62:63], v[132:133]
	v_fma_f32 v136, v166, v108, v168
	v_pk_fma_f32 v[36:37], v[64:65], v[166:167], v[126:127] op_sel_hi:[1,0,1]
	v_pk_fma_f32 v[38:39], v[66:67], v[166:167], v[128:129] op_sel_hi:[1,0,1]
	v_pk_fma_f32 v[32:33], v[68:69], v[166:167], v[130:131] op_sel_hi:[1,0,1]
	v_pk_fma_f32 v[34:35], v[70:71], v[166:167], v[132:133] op_sel_hi:[1,0,1]
	v_fma_f32 v136, v94, v109, v136
	ds_write_b32 v95, v136 offset:512
	ds_read_b128 v[40:43], v120 offset:7680
	ds_read_b128 v[44:47], v120 offset:7696
	ds_read_b128 v[48:51], v120 offset:7936
	ds_read_b128 v[52:55], v120 offset:7952
	ds_read_b128 v[56:59], v120 offset:8192
	ds_read_b128 v[60:63], v120 offset:8208
	ds_read_b128 v[64:67], v120 offset:8448
	ds_read_b128 v[68:71], v120 offset:8464
	ds_read_b128 v[72:75], v120 offset:8704
	ds_read_b128 v[76:79], v120 offset:8720
	ds_read_b32 v94, v96 offset:22016
	ds_read_b64 v[108:109], v121 offset:24672
	s_waitcnt lgkmcnt(12)
	v_pk_mul_f32 v[122:123], v[38:39], v[192:193]
	v_pk_mul_f32 v[124:125], v[38:39], v[200:201]
	v_pk_fma_f32 v[122:123], v[36:37], v[190:191], v[122:123]
	v_pk_fma_f32 v[124:125], v[36:37], v[198:199], v[124:125]
	v_pk_fma_f32 v[122:123], v[32:33], v[194:195], v[122:123]
	v_pk_fma_f32 v[124:125], v[32:33], v[202:203], v[124:125]
	v_pk_fma_f32 v[122:123], v[34:35], v[196:197], v[122:123]
	v_pk_fma_f32 v[124:125], v[34:35], v[204:205], v[124:125]
	v_pk_mul_f32 v[126:127], v[222:223], v[230:231] op_sel_hi:[1,0]
	v_add_f32_e32 v166, v122, v123
	v_add_f32_e32 v168, v124, v125
	v_pk_mul_f32 v[128:129], v[224:225], v[230:231] op_sel_hi:[1,0]
	v_pk_mul_f32 v[130:131], v[226:227], v[230:231] op_sel_hi:[1,0]
	v_add_f32_dpp v166, v166, v166 quad_perm:[1,0,3,2] row_mask:0xf bank_mask:0xf bound_ctrl:1
	v_add_f32_dpp v168, v168, v168 quad_perm:[1,0,3,2] row_mask:0xf bank_mask:0xf bound_ctrl:1
	v_pk_mul_f32 v[132:133], v[228:229], v[230:231] op_sel_hi:[1,0]
	v_pk_fma_f32 v[126:127], v[36:37], v[206:207], v[126:127]
	v_add_f32_dpp v166, v166, v166 quad_perm:[2,3,0,1] row_mask:0xf bank_mask:0xf bound_ctrl:1
	v_add_f32_dpp v168, v168, v168 quad_perm:[2,3,0,1] row_mask:0xf bank_mask:0xf bound_ctrl:1
	v_pk_fma_f32 v[128:129], v[38:39], v[208:209], v[128:129]
	v_pk_fma_f32 v[130:131], v[32:33], v[210:211], v[130:131]
	v_add_f32_dpp v166, v166, v166 row_half_mirror row_mask:0xf bank_mask:0xf bound_ctrl:1
	v_add_f32_dpp v168, v168, v168 row_half_mirror row_mask:0xf bank_mask:0xf bound_ctrl:1
	v_pk_fma_f32 v[132:133], v[34:35], v[212:213], v[132:133]
	v_fma_f32 v136, v166, v232, v168
	v_pk_fma_f32 v[36:37], v[214:215], v[166:167], v[126:127] op_sel_hi:[1,0,1]
	v_pk_fma_f32 v[38:39], v[216:217], v[166:167], v[128:129] op_sel_hi:[1,0,1]
	v_pk_fma_f32 v[32:33], v[218:219], v[166:167], v[130:131] op_sel_hi:[1,0,1]
	v_pk_fma_f32 v[34:35], v[220:221], v[166:167], v[132:133] op_sel_hi:[1,0,1]
	v_fma_f32 v136, v230, v233, v136
	ds_write_b32 v95, v136 offset:640
	ds_read_b128 v[190:193], v120 offset:8960
	ds_read_b128 v[194:197], v120 offset:8976
	ds_read_b128 v[198:201], v120 offset:9216
	ds_read_b128 v[202:205], v120 offset:9232
	ds_read_b128 v[206:209], v120 offset:9472
	ds_read_b128 v[210:213], v120 offset:9488
	ds_read_b128 v[214:217], v120 offset:9728
	ds_read_b128 v[218:221], v120 offset:9744
	ds_read_b128 v[222:225], v120 offset:9984
	ds_read_b128 v[226:229], v120 offset:10000
	ds_read_b32 v230, v96 offset:22272
	ds_read_b64 v[232:233], v121 offset:24688
	s_waitcnt lgkmcnt(12)
; #define SC_LOAD(t) { _Pragma("unroll") for (int q = 0; q < 5; ++q) { n[2 * q] = *(const LAS f32x4*)(opb + (t) * 320 + q * 64); n[2 * q + 1] = *(const LAS f32x4*)(opb + (t) * 320 + q * 64 + 4); } \
;                      nv = vvb[(t) * 64]; nbk = *(const LAS f32x2*)(scb + (t) * 4); }
; DI void scan_item(const __attribute__((address_space(4))) Args& a, LAS unsigned char* lds, int ws_, bool is_prompt, int seq, int h, int half, bool dry = false) {
;     ...
;         SC_LOAD(0)
; #pragma unroll 4
;         for (int t = 0; t < SC_CH; ++t) {
;             f32x4 c[10];
; #pragma unroll
;             for (int q = 0; q < 10; ++q) c[q] = n[q];
;             const float v0 = nv; const f32x2 bk = nbk;
;             SC_LOAD(t + 1)
;             __builtin_amdgcn_sched_barrier(0);
;             f32x2 aA = sp[0] * c[0].xy, aY = sp[0] * c[2].xy;
;             aA = sp[1] * c[0].zw + aA; aY = sp[1] * c[2].zw + aY;
;             aA = sp[2] * c[1].xy + aA; aY = sp[2] * c[3].xy + aY;
;             aA = sp[3] * c[1].zw + aA; aY = sp[3] * c[3].zw + aY;
;             float da = aA.x + aA.y, dy = aY.x + aY.y;
;             asm("s_nop 1\n\t"
;                 "v_add_f32_dpp %0, %0, %0 quad_perm:[1,0,3,2] row_mask:0xf bank_mask:0xf bound_ctrl:1\n\t"
;                 "v_add_f32_dpp %1, %1, %1 quad_perm:[1,0,3,2] row_mask:0xf bank_mask:0xf bound_ctrl:1\n\t"
;                 "s_nop 0\n\t"
;                 "v_add_f32_dpp %0, %0, %0 quad_perm:[2,3,0,1] row_mask:0xf bank_mask:0xf bound_ctrl:1\n\t"
;                 "v_add_f32_dpp %1, %1, %1 quad_perm:[2,3,0,1] row_mask:0xf bank_mask:0xf bound_ctrl:1\n\t"
;                 "s_nop 0\n\t"
;                 "v_add_f32_dpp %0, %0, %0 row_half_mirror row_mask:0xf bank_mask:0xf bound_ctrl:1\n\t"
;                 "v_add_f32_dpp %1, %1, %1 row_half_mirror row_mask:0xf bank_mask:0xf bound_ctrl:1"
;                 : "+v"(da), "+v"(dy));
;             {
;                 f32x2 t0;
;                 t0 = c[8].xy * v0; t0 = c[6].xy * da + t0; sp[0] = sp[0] * c[4].xy + t0;
;                 t0 = c[8].zw * v0; t0 = c[6].zw * da + t0; sp[1] = sp[1] * c[4].zw + t0;
;                 t0 = c[9].xy * v0; t0 = c[7].xy * da + t0; sp[2] = sp[2] * c[5].xy + t0;
;                 t0 = c[9].zw * v0; t0 = c[7].zw * da + t0; sp[3] = sp[3] * c[5].zw + t0;
;             }
;             ybb[t * 32] = dy + da * bk.x + v0 * bk.y;
;         }
	v_pk_mul_f32 v[122:123], v[38:39], v[42:43]
	v_pk_mul_f32 v[124:125], v[38:39], v[50:51]
	v_pk_fma_f32 v[122:123], v[36:37], v[40:41], v[122:123]
	v_pk_fma_f32 v[124:125], v[36:37], v[48:49], v[124:125]
	v_pk_fma_f32 v[122:123], v[32:33], v[44:45], v[122:123]
	v_pk_fma_f32 v[124:125], v[32:33], v[52:53], v[124:125]
	v_pk_fma_f32 v[122:123], v[34:35], v[46:47], v[122:123]
	v_pk_fma_f32 v[124:125], v[34:35], v[54:55], v[124:125]
	v_pk_mul_f32 v[126:127], v[72:73], v[94:95] op_sel_hi:[1,0]
	v_add_f32_e32 v166, v122, v123
	v_add_f32_e32 v168, v124, v125
	v_pk_mul_f32 v[128:129], v[74:75], v[94:95] op_sel_hi:[1,0]
	v_pk_mul_f32 v[130:131], v[76:77], v[94:95] op_sel_hi:[1,0]
	v_add_f32_dpp v166, v166, v166 quad_perm:[1,0,3,2] row_mask:0xf bank_mask:0xf bound_ctrl:1
	v_add_f32_dpp v168, v168, v168 quad_perm:[1,0,3,2] row_mask:0xf bank_mask:0xf bound_ctrl:1
	v_pk_mul_f32 v[132:133], v[78:79], v[94:95] op_sel_hi:[1,0]
	v_pk_fma_f32 v[126:127], v[36:37], v[56:57], v[126:127]
	v_add_f32_dpp v166, v166, v166 quad_perm:[2,3,0,1] row_mask:0xf bank_mask:0xf bound_ctrl:1
	v_add_f32_dpp v168, v168, v168 quad_perm:[2,3,0,1] row_mask:0xf bank_mask:0xf bound_ctrl:1
	v_pk_fma_f32 v[128:129], v[38:39], v[58:59], v[128:129]
	v_pk_fma_f32 v[130:131], v[32:33], v[60:61], v[130:131]
	v_add_f32_dpp v166, v166, v166 row_half_mirror row_mask:0xf bank_mask:0xf bound_ctrl:1
	v_add_f32_dpp v168, v168, v168 row_half_mirror row_mask:0xf bank_mask:0xf bound_ctrl:1
	v_pk_fma_f32 v[132:133], v[34:35], v[62:63], v[132:133]
	v_fma_f32 v136, v166, v108, v168
	v_pk_fma_f32 v[36:37], v[64:65], v[166:167], v[126:127] op_sel_hi:[1,0,1]
	v_pk_fma_f32 v[38:39], v[66:67], v[166:167], v[128:129] op_sel_hi:[1,0,1]
	v_pk_fma_f32 v[32:33], v[68:69], v[166:167], v[130:131] op_sel_hi:[1,0,1]
	v_pk_fma_f32 v[34:35], v[70:71], v[166:167], v[132:133] op_sel_hi:[1,0,1]
	v_fma_f32 v136, v94, v109, v136
	ds_write_b32 v95, v136 offset:768
	ds_read_b128 v[40:43], v120 offset:10240
	ds_read_b128 v[44:47], v120 offset:10256
	ds_read_b128 v[48:51], v120 offset:10496
	ds_read_b128 v[52:55], v120 offset:10512
	ds_read_b128 v[56:59], v120 offset:10752
	ds_read_b128 v[60:63], v120 offset:10768
	ds_read_b128 v[64:67], v120 offset:11008
	ds_read_b128 v[68:71], v120 offset:11024
	ds_read_b128 v[72:75], v120 offset:11264
	ds_read_b128 v[76:79], v120 offset:11280
	ds_read_b32 v94, v96 offset:22528
	ds_read_b64 v[108:109], v121 offset:24704
	s_waitcnt lgkmcnt(12)
	v_pk_mul_f32 v[122:123], v[38:39], v[192:193]
	v_pk_mul_f32 v[124:125], v[38:39], v[200:201]
	v_pk_fma_f32 v[122:123], v[36:37], v[190:191], v[122:123]
	v_pk_fma_f32 v[124:125], v[36:37], v[198:199], v[124:125]
	v_pk_fma_f32 v[122:123], v[32:33], v[194:195], v[122:123]
	v_pk_fma_f32 v[124:125], v[32:33], v[202:203], v[124:125]
	v_pk_fma_f32 v[122:123], v[34:35], v[196:197], v[122:123]
	v_pk_fma_f32 v[124:125], v[34:35], v[204:205], v[124:125]
	v_pk_mul_f32 v[126:127], v[222:223], v[230:231] op_sel_hi:[1,0]
	v_add_f32_e32 v166, v122, v123
	v_add_f32_e32 v168, v124, v125
	v_pk_mul_f32 v[128:129], v[224:225], v[230:231] op_sel_hi:[1,0]
	v_pk_mul_f32 v[130:131], v[226:227], v[230:231] op_sel_hi:[1,0]
	v_add_f32_dpp v166, v166, v166 quad_perm:[1,0,3,2] row_mask:0xf bank_mask:0xf bound_ctrl:1
	v_add_f32_dpp v168, v168, v168 quad_perm:[1,0,3,2] row_mask:0xf bank_mask:0xf bound_ctrl:1
	v_pk_mul_f32 v[132:133], v[228:229], v[230:231] op_sel_hi:[1,0]
	v_pk_fma_f32 v[126:127], v[36:37], v[206:207], v[126:127]
	v_add_f32_dpp v166, v166, v166 quad_perm:[2,3,0,1] row_mask:0xf bank_mask:0xf bound_ctrl:1
	v_add_f32_dpp v168, v168, v168 quad_perm:[2,3,0,1] row_mask:0xf bank_mask:0xf bound_ctrl:1
	v_pk_fma_f32 v[128:129], v[38:39], v[208:209], v[128:129]
	v_pk_fma_f32 v[130:131], v[32:33], v[210:211], v[130:131]
	v_add_f32_dpp v166, v166, v166 row_half_mirror row_mask:0xf bank_mask:0xf bound_ctrl:1
	v_add_f32_dpp v168, v168, v168 row_half_mirror row_mask:0xf bank_mask:0xf bound_ctrl:1
	v_pk_fma_f32 v[132:133], v[34:35], v[212:213], v[132:133]
	v_fma_f32 v136, v166, v232, v168
	v_pk_fma_f32 v[36:37], v[214:215], v[166:167], v[126:127] op_sel_hi:[1,0,1]
	v_pk_fma_f32 v[38:39], v[216:217], v[166:167], v[128:129] op_sel_hi:[1,0,1]
	v_pk_fma_f32 v[32:33], v[218:219], v[166:167], v[130:131] op_sel_hi:[1,0,1]
	v_pk_fma_f32 v[34:35], v[220:221], v[166:167], v[132:133] op_sel_hi:[1,0,1]
	v_fma_f32 v136, v230, v233, v136
	ds_write_b32 v95, v136 offset:896
	ds_read_b128 v[190:193], v120 offset:11520
	ds_read_b128 v[194:197], v120 offset:11536
	ds_read_b128 v[198:201], v120 offset:11776
	ds_read_b128 v[202:205], v120 offset:11792
	ds_read_b128 v[206:209], v120 offset:12032
	ds_read_b128 v[210:213], v120 offset:12048
	ds_read_b128 v[214:217], v120 offset:12288
	ds_read_b128 v[218:221], v120 offset:12304
	ds_read_b128 v[222:225], v120 offset:12544
	ds_read_b128 v[226:229], v120 offset:12560
	ds_read_b32 v230, v96 offset:22784
	ds_read_b64 v[232:233], v121 offset:24720
	s_waitcnt lgkmcnt(12)
; #define SC_LOAD(t) { _Pragma("unroll") for (int q = 0; q < 5; ++q) { n[2 * q] = *(const LAS f32x4*)(opb + (t) * 320 + q * 64); n[2 * q + 1] = *(const LAS f32x4*)(opb + (t) * 320 + q * 64 + 4); } \
;                      nv = vvb[(t) * 64]; nbk = *(const LAS f32x2*)(scb + (t) * 4); }
; DI void scan_item(const __attribute__((address_space(4))) Args& a, LAS unsigned char* lds, int ws_, bool is_prompt, int seq, int h, int half, bool dry = false) {
;     ...
;         for (int t = 0; t < SC_CH; ++t) {
;             f32x4 c[10];
; #pragma unroll
;             for (int q = 0; q < 10; ++q) c[q] = n[q];
;             const float v0 = nv; const f32x2 bk = nbk;
;             SC_LOAD(t + 1)
;             __builtin_amdgcn_sched_barrier(0);
;             f32x2 aA = sp[0] * c[0].xy, aY = sp[0] * c[2].xy;
;             aA = sp[1] * c[0].zw + aA; aY = sp[1] * c[2].zw + aY;
;             aA = sp[2] * c[1].xy + aA; aY = sp[2] * c[3].xy + aY;
;             aA = sp[3] * c[1].zw + aA; aY = sp[3] * c[3].zw + aY;
;             float da = aA.x + aA.y, dy = aY.x + aY.y;
;             asm("s_nop 1\n\t"
;                 "v_add_f32_dpp %0, %0, %0 quad_perm:[1,0,3,2] row_mask:0xf bank_mask:0xf bound_ctrl:1\n\t"
;                 "v_add_f32_dpp %1, %1, %1 quad_perm:[1,0,3,2] row_mask:0xf bank_mask:0xf bound_ctrl:1\n\t"
;                 "s_nop 0\n\t"
;                 "v_add_f32_dpp %0, %0, %0 quad_perm:[2,3,0,1] row_mask:0xf bank_mask:0xf bound_ctrl:1\n\t"
;                 "v_add_f32_dpp %1, %1, %1 quad_perm:[2,3,0,1] row_mask:0xf bank_mask:0xf bound_ctrl:1\n\t"
;                 "s_nop 0\n\t"
;                 "v_add_f32_dpp %0, %0, %0 row_half_mirror row_mask:0xf bank_mask:0xf bound_ctrl:1\n\t"
;                 "v_add_f32_dpp %1, %1, %1 row_half_mirror row_mask:0xf bank_mask:0xf bound_ctrl:1"
;                 : "+v"(da), "+v"(dy));
;             {
;                 f32x2 t0;
;                 t0 = c[8].xy * v0; t0 = c[6].xy * da + t0; sp[0] = sp[0] * c[4].xy + t0;
;                 t0 = c[8].zw * v0; t0 = c[6].zw * da + t0; sp[1] = sp[1] * c[4].zw + t0;
;                 t0 = c[9].xy * v0; t0 = c[7].xy * da + t0; sp[2] = sp[2] * c[5].xy + t0;
;                 t0 = c[9].zw * v0; t0 = c[7].zw * da + t0; sp[3] = sp[3] * c[5].zw + t0;
;             }
;             ybb[t * 32] = dy + da * bk.x + v0 * bk.y;
	v_pk_mul_f32 v[122:123], v[38:39], v[42:43]
	v_pk_mul_f32 v[124:125], v[38:39], v[50:51]
	v_pk_fma_f32 v[122:123], v[36:37], v[40:41], v[122:123]
	v_pk_fma_f32 v[124:125], v[36:37], v[48:49], v[124:125]
	v_pk_fma_f32 v[122:123], v[32:33], v[44:45], v[122:123]
	v_pk_fma_f32 v[124:125], v[32:33], v[52:53], v[124:125]
	v_pk_fma_f32 v[122:123], v[34:35], v[46:47], v[122:123]
	v_pk_fma_f32 v[124:125], v[34:35], v[54:55], v[124:125]
	v_pk_mul_f32 v[126:127], v[72:73], v[94:95] op_sel_hi:[1,0]
	v_add_f32_e32 v166, v122, v123
	v_add_f32_e32 v168, v124, v125
	v_pk_mul_f32 v[128:129], v[74:75], v[94:95] op_sel_hi:[1,0]
	v_pk_mul_f32 v[130:131], v[76:77], v[94:95] op_sel_hi:[1,0]
	v_add_f32_dpp v166, v166, v166 quad_perm:[1,0,3,2] row_mask:0xf bank_mask:0xf bound_ctrl:1
	v_add_f32_dpp v168, v168, v168 quad_perm:[1,0,3,2] row_mask:0xf bank_mask:0xf bound_ctrl:1
	v_pk_mul_f32 v[132:133], v[78:79], v[94:95] op_sel_hi:[1,0]
	v_pk_fma_f32 v[126:127], v[36:37], v[56:57], v[126:127]
	v_add_f32_dpp v166, v166, v166 quad_perm:[2,3,0,1] row_mask:0xf bank_mask:0xf bound_ctrl:1
	v_add_f32_dpp v168, v168, v168 quad_perm:[2,3,0,1] row_mask:0xf bank_mask:0xf bound_ctrl:1
	v_pk_fma_f32 v[128:129], v[38:39], v[58:59], v[128:129]
	v_pk_fma_f32 v[130:131], v[32:33], v[60:61], v[130:131]
	v_add_f32_dpp v166, v166, v166 row_half_mirror row_mask:0xf bank_mask:0xf bound_ctrl:1
	v_add_f32_dpp v168, v168, v168 row_half_mirror row_mask:0xf bank_mask:0xf bound_ctrl:1
	v_pk_fma_f32 v[132:133], v[34:35], v[62:63], v[132:133]
	v_fma_f32 v136, v166, v108, v168
	v_pk_fma_f32 v[36:37], v[64:65], v[166:167], v[126:127] op_sel_hi:[1,0,1]
	v_pk_fma_f32 v[38:39], v[66:67], v[166:167], v[128:129] op_sel_hi:[1,0,1]
	v_pk_fma_f32 v[32:33], v[68:69], v[166:167], v[130:131] op_sel_hi:[1,0,1]
	v_pk_fma_f32 v[34:35], v[70:71], v[166:167], v[132:133] op_sel_hi:[1,0,1]
	v_fma_f32 v136, v94, v109, v136
	ds_write_b32 v95, v136 offset:1024
	ds_read_b128 v[40:43], v120 offset:12800
	ds_read_b128 v[44:47], v120 offset:12816
	ds_read_b128 v[48:51], v120 offset:13056
	ds_read_b128 v[52:55], v120 offset:13072
	ds_read_b128 v[56:59], v120 offset:13312
	ds_read_b128 v[60:63], v120 offset:13328
	ds_read_b128 v[64:67], v120 offset:13568
	ds_read_b128 v[68:71], v120 offset:13584
	ds_read_b128 v[72:75], v120 offset:13824
	ds_read_b128 v[76:79], v120 offset:13840
	ds_read_b32 v94, v96 offset:23040
	ds_read_b64 v[108:109], v121 offset:24736
	s_waitcnt lgkmcnt(12)
	v_pk_mul_f32 v[122:123], v[38:39], v[192:193]
	v_pk_mul_f32 v[124:125], v[38:39], v[200:201]
	v_pk_fma_f32 v[122:123], v[36:37], v[190:191], v[122:123]
	v_pk_fma_f32 v[124:125], v[36:37], v[198:199], v[124:125]
	v_pk_fma_f32 v[122:123], v[32:33], v[194:195], v[122:123]
	v_pk_fma_f32 v[124:125], v[32:33], v[202:203], v[124:125]
	v_pk_fma_f32 v[122:123], v[34:35], v[196:197], v[122:123]
	v_pk_fma_f32 v[124:125], v[34:35], v[204:205], v[124:125]
	v_pk_mul_f32 v[126:127], v[222:223], v[230:231] op_sel_hi:[1,0]
	v_add_f32_e32 v166, v122, v123
	v_add_f32_e32 v168, v124, v125
	v_pk_mul_f32 v[128:129], v[224:225], v[230:231] op_sel_hi:[1,0]
	v_pk_mul_f32 v[130:131], v[226:227], v[230:231] op_sel_hi:[1,0]
	v_add_f32_dpp v166, v166, v166 quad_perm:[1,0,3,2] row_mask:0xf bank_mask:0xf bound_ctrl:1
	v_add_f32_dpp v168, v168, v168 quad_perm:[1,0,3,2] row_mask:0xf bank_mask:0xf bound_ctrl:1
	v_pk_mul_f32 v[132:133], v[228:229], v[230:231] op_sel_hi:[1,0]
	v_pk_fma_f32 v[126:127], v[36:37], v[206:207], v[126:127]
	v_add_f32_dpp v166, v166, v166 quad_perm:[2,3,0,1] row_mask:0xf bank_mask:0xf bound_ctrl:1
	v_add_f32_dpp v168, v168, v168 quad_perm:[2,3,0,1] row_mask:0xf bank_mask:0xf bound_ctrl:1
	v_pk_fma_f32 v[128:129], v[38:39], v[208:209], v[128:129]
	v_pk_fma_f32 v[130:131], v[32:33], v[210:211], v[130:131]
	v_add_f32_dpp v166, v166, v166 row_half_mirror row_mask:0xf bank_mask:0xf bound_ctrl:1
	v_add_f32_dpp v168, v168, v168 row_half_mirror row_mask:0xf bank_mask:0xf bound_ctrl:1
	v_pk_fma_f32 v[132:133], v[34:35], v[212:213], v[132:133]
	v_fma_f32 v136, v166, v232, v168
	v_pk_fma_f32 v[36:37], v[214:215], v[166:167], v[126:127] op_sel_hi:[1,0,1]
	v_pk_fma_f32 v[38:39], v[216:217], v[166:167], v[128:129] op_sel_hi:[1,0,1]
	v_pk_fma_f32 v[32:33], v[218:219], v[166:167], v[130:131] op_sel_hi:[1,0,1]
	v_pk_fma_f32 v[34:35], v[220:221], v[166:167], v[132:133] op_sel_hi:[1,0,1]
	v_fma_f32 v136, v230, v233, v136
	ds_write_b32 v95, v136 offset:1152
	ds_read_b128 v[190:193], v120 offset:14080
	ds_read_b128 v[194:197], v120 offset:14096
	ds_read_b128 v[198:201], v120 offset:14336
	ds_read_b128 v[202:205], v120 offset:14352
	ds_read_b128 v[206:209], v120 offset:14592
	ds_read_b128 v[210:213], v120 offset:14608
	ds_read_b128 v[214:217], v120 offset:14848
	ds_read_b128 v[218:221], v120 offset:14864
	ds_read_b128 v[222:225], v120 offset:15104
	ds_read_b128 v[226:229], v120 offset:15120
	ds_read_b32 v230, v96 offset:23296
	ds_read_b64 v[232:233], v121 offset:24752
	s_waitcnt lgkmcnt(12)
; #define SC_LOAD(t) { _Pragma("unroll") for (int q = 0; q < 5; ++q) { n[2 * q] = *(const LAS f32x4*)(opb + (t) * 320 + q * 64); n[2 * q + 1] = *(const LAS f32x4*)(opb + (t) * 320 + q * 64 + 4); } \
;                      nv = vvb[(t) * 64]; nbk = *(const LAS f32x2*)(scb + (t) * 4); }
; DI void scan_item(const __attribute__((address_space(4))) Args& a, LAS unsigned char* lds, int ws_, bool is_prompt, int seq, int h, int half, bool dry = false) {
;     ...
;         for (int t = 0; t < SC_CH; ++t) {
;             f32x4 c[10];
; #pragma unroll
;             for (int q = 0; q < 10; ++q) c[q] = n[q];
;             const float v0 = nv; const f32x2 bk = nbk;
;             SC_LOAD(t + 1)
;             __builtin_amdgcn_sched_barrier(0);
;             f32x2 aA = sp[0] * c[0].xy, aY = sp[0] * c[2].xy;
;             aA = sp[1] * c[0].zw + aA; aY = sp[1] * c[2].zw + aY;
;             aA = sp[2] * c[1].xy + aA; aY = sp[2] * c[3].xy + aY;
;             aA = sp[3] * c[1].zw + aA; aY = sp[3] * c[3].zw + aY;
;             float da = aA.x + aA.y, dy = aY.x + aY.y;
;             asm("s_nop 1\n\t"
;                 "v_add_f32_dpp %0, %0, %0 quad_perm:[1,0,3,2] row_mask:0xf bank_mask:0xf bound_ctrl:1\n\t"
;                 "v_add_f32_dpp %1, %1, %1 quad_perm:[1,0,3,2] row_mask:0xf bank_mask:0xf bound_ctrl:1\n\t"
;                 "s_nop 0\n\t"
;                 "v_add_f32_dpp %0, %0, %0 quad_perm:[2,3,0,1] row_mask:0xf bank_mask:0xf bound_ctrl:1\n\t"
;                 "v_add_f32_dpp %1, %1, %1 quad_perm:[2,3,0,1] row_mask:0xf bank_mask:0xf bound_ctrl:1\n\t"
;                 "s_nop 0\n\t"
;                 "v_add_f32_dpp %0, %0, %0 row_half_mirror row_mask:0xf bank_mask:0xf bound_ctrl:1\n\t"
;                 "v_add_f32_dpp %1, %1, %1 row_half_mirror row_mask:0xf bank_mask:0xf bound_ctrl:1"
;                 : "+v"(da), "+v"(dy));
;             {
;                 f32x2 t0;
;                 t0 = c[8].xy * v0; t0 = c[6].xy * da + t0; sp[0] = sp[0] * c[4].xy + t0;
;                 t0 = c[8].zw * v0; t0 = c[6].zw * da + t0; sp[1] = sp[1] * c[4].zw + t0;
;                 t0 = c[9].xy * v0; t0 = c[7].xy * da + t0; sp[2] = sp[2] * c[5].xy + t0;
;                 t0 = c[9].zw * v0; t0 = c[7].zw * da + t0; sp[3] = sp[3] * c[5].zw + t0;
;             }
;             ybb[t * 32] = dy + da * bk.x + v0 * bk.y;
	v_pk_mul_f32 v[122:123], v[38:39], v[42:43]
	v_pk_mul_f32 v[124:125], v[38:39], v[50:51]
	v_pk_fma_f32 v[122:123], v[36:37], v[40:41], v[122:123]
	v_pk_fma_f32 v[124:125], v[36:37], v[48:49], v[124:125]
	v_pk_fma_f32 v[122:123], v[32:33], v[44:45], v[122:123]
	v_pk_fma_f32 v[124:125], v[32:33], v[52:53], v[124:125]
	v_pk_fma_f32 v[122:123], v[34:35], v[46:47], v[122:123]
	v_pk_fma_f32 v[124:125], v[34:35], v[54:55], v[124:125]
	v_pk_mul_f32 v[126:127], v[72:73], v[94:95] op_sel_hi:[1,0]
	v_add_f32_e32 v166, v122, v123
	v_add_f32_e32 v168, v124, v125
	v_pk_mul_f32 v[128:129], v[74:75], v[94:95] op_sel_hi:[1,0]
	v_pk_mul_f32 v[130:131], v[76:77], v[94:95] op_sel_hi:[1,0]
	v_add_f32_dpp v166, v166, v166 quad_perm:[1,0,3,2] row_mask:0xf bank_mask:0xf bound_ctrl:1
	v_add_f32_dpp v168, v168, v168 quad_perm:[1,0,3,2] row_mask:0xf bank_mask:0xf bound_ctrl:1
	v_pk_mul_f32 v[132:133], v[78:79], v[94:95] op_sel_hi:[1,0]
	v_pk_fma_f32 v[126:127], v[36:37], v[56:57], v[126:127]
	v_add_f32_dpp v166, v166, v166 quad_perm:[2,3,0,1] row_mask:0xf bank_mask:0xf bound_ctrl:1
	v_add_f32_dpp v168, v168, v168 quad_perm:[2,3,0,1] row_mask:0xf bank_mask:0xf bound_ctrl:1
	v_pk_fma_f32 v[128:129], v[38:39], v[58:59], v[128:129]
	v_pk_fma_f32 v[130:131], v[32:33], v[60:61], v[130:131]
	v_add_f32_dpp v166, v166, v166 row_half_mirror row_mask:0xf bank_mask:0xf bound_ctrl:1
	v_add_f32_dpp v168, v168, v168 row_half_mirror row_mask:0xf bank_mask:0xf bound_ctrl:1
	v_pk_fma_f32 v[132:133], v[34:35], v[62:63], v[132:133]
	v_fma_f32 v136, v166, v108, v168
	v_pk_fma_f32 v[36:37], v[64:65], v[166:167], v[126:127] op_sel_hi:[1,0,1]
	v_pk_fma_f32 v[38:39], v[66:67], v[166:167], v[128:129] op_sel_hi:[1,0,1]
	v_pk_fma_f32 v[32:33], v[68:69], v[166:167], v[130:131] op_sel_hi:[1,0,1]
	v_pk_fma_f32 v[34:35], v[70:71], v[166:167], v[132:133] op_sel_hi:[1,0,1]
	v_fma_f32 v136, v94, v109, v136
	ds_write_b32 v95, v136 offset:1280
	ds_read_b128 v[40:43], v120 offset:15360
	ds_read_b128 v[44:47], v120 offset:15376
	ds_read_b128 v[48:51], v120 offset:15616
	ds_read_b128 v[52:55], v120 offset:15632
	ds_read_b128 v[56:59], v120 offset:15872
	ds_read_b128 v[60:63], v120 offset:15888
	ds_read_b128 v[64:67], v120 offset:16128
	ds_read_b128 v[68:71], v120 offset:16144
	ds_read_b128 v[72:75], v120 offset:16384
	ds_read_b128 v[76:79], v120 offset:16400
	ds_read_b32 v94, v96 offset:23552
	ds_read_b64 v[108:109], v121 offset:24768
	s_waitcnt lgkmcnt(12)
	v_pk_mul_f32 v[122:123], v[38:39], v[192:193]
	v_pk_mul_f32 v[124:125], v[38:39], v[200:201]
	v_pk_fma_f32 v[122:123], v[36:37], v[190:191], v[122:123]
	v_pk_fma_f32 v[124:125], v[36:37], v[198:199], v[124:125]
	v_pk_fma_f32 v[122:123], v[32:33], v[194:195], v[122:123]
	v_pk_fma_f32 v[124:125], v[32:33], v[202:203], v[124:125]
	v_pk_fma_f32 v[122:123], v[34:35], v[196:197], v[122:123]
	v_pk_fma_f32 v[124:125], v[34:35], v[204:205], v[124:125]
	v_pk_mul_f32 v[126:127], v[222:223], v[230:231] op_sel_hi:[1,0]
	v_add_f32_e32 v166, v122, v123
	v_add_f32_e32 v168, v124, v125
	v_pk_mul_f32 v[128:129], v[224:225], v[230:231] op_sel_hi:[1,0]
	v_pk_mul_f32 v[130:131], v[226:227], v[230:231] op_sel_hi:[1,0]
	v_add_f32_dpp v166, v166, v166 quad_perm:[1,0,3,2] row_mask:0xf bank_mask:0xf bound_ctrl:1
	v_add_f32_dpp v168, v168, v168 quad_perm:[1,0,3,2] row_mask:0xf bank_mask:0xf bound_ctrl:1
	v_pk_mul_f32 v[132:133], v[228:229], v[230:231] op_sel_hi:[1,0]
	v_pk_fma_f32 v[126:127], v[36:37], v[206:207], v[126:127]
	v_add_f32_dpp v166, v166, v166 quad_perm:[2,3,0,1] row_mask:0xf bank_mask:0xf bound_ctrl:1
	v_add_f32_dpp v168, v168, v168 quad_perm:[2,3,0,1] row_mask:0xf bank_mask:0xf bound_ctrl:1
	v_pk_fma_f32 v[128:129], v[38:39], v[208:209], v[128:129]
	v_pk_fma_f32 v[130:131], v[32:33], v[210:211], v[130:131]
	v_add_f32_dpp v166, v166, v166 row_half_mirror row_mask:0xf bank_mask:0xf bound_ctrl:1
	v_add_f32_dpp v168, v168, v168 row_half_mirror row_mask:0xf bank_mask:0xf bound_ctrl:1
	v_pk_fma_f32 v[132:133], v[34:35], v[212:213], v[132:133]
	v_fma_f32 v136, v166, v232, v168
	v_pk_fma_f32 v[36:37], v[214:215], v[166:167], v[126:127] op_sel_hi:[1,0,1]
	v_pk_fma_f32 v[38:39], v[216:217], v[166:167], v[128:129] op_sel_hi:[1,0,1]
	v_pk_fma_f32 v[32:33], v[218:219], v[166:167], v[130:131] op_sel_hi:[1,0,1]
	v_pk_fma_f32 v[34:35], v[220:221], v[166:167], v[132:133] op_sel_hi:[1,0,1]
	v_fma_f32 v136, v230, v233, v136
	ds_write_b32 v95, v136 offset:1408
	ds_read_b128 v[190:193], v120 offset:16640
	ds_read_b128 v[194:197], v120 offset:16656
	ds_read_b128 v[198:201], v120 offset:16896
	ds_read_b128 v[202:205], v120 offset:16912
	ds_read_b128 v[206:209], v120 offset:17152
	ds_read_b128 v[210:213], v120 offset:17168
	ds_read_b128 v[214:217], v120 offset:17408
	ds_read_b128 v[218:221], v120 offset:17424
	ds_read_b128 v[222:225], v120 offset:17664
	ds_read_b128 v[226:229], v120 offset:17680
	ds_read_b32 v230, v96 offset:23808
	ds_read_b64 v[232:233], v121 offset:24784
	s_waitcnt lgkmcnt(12)
; #define SC_LOAD(t) { _Pragma("unroll") for (int q = 0; q < 5; ++q) { n[2 * q] = *(const LAS f32x4*)(opb + (t) * 320 + q * 64); n[2 * q + 1] = *(const LAS f32x4*)(opb + (t) * 320 + q * 64 + 4); } \
;                      nv = vvb[(t) * 64]; nbk = *(const LAS f32x2*)(scb + (t) * 4); }
; DI void scan_item(const __attribute__((address_space(4))) Args& a, LAS unsigned char* lds, int ws_, bool is_prompt, int seq, int h, int half, bool dry = false) {
;     ...
;         for (int t = 0; t < SC_CH; ++t) {
;             f32x4 c[10];
; #pragma unroll
;             for (int q = 0; q < 10; ++q) c[q] = n[q];
;             const float v0 = nv; const f32x2 bk = nbk;
;             SC_LOAD(t + 1)
;             __builtin_amdgcn_sched_barrier(0);
;             f32x2 aA = sp[0] * c[0].xy, aY = sp[0] * c[2].xy;
;             aA = sp[1] * c[0].zw + aA; aY = sp[1] * c[2].zw + aY;
;             aA = sp[2] * c[1].xy + aA; aY = sp[2] * c[3].xy + aY;
;             aA = sp[3] * c[1].zw + aA; aY = sp[3] * c[3].zw + aY;
;             float da = aA.x + aA.y, dy = aY.x + aY.y;
;             asm("s_nop 1\n\t"
;                 "v_add_f32_dpp %0, %0, %0 quad_perm:[1,0,3,2] row_mask:0xf bank_mask:0xf bound_ctrl:1\n\t"
;                 "v_add_f32_dpp %1, %1, %1 quad_perm:[1,0,3,2] row_mask:0xf bank_mask:0xf bound_ctrl:1\n\t"
;                 "s_nop 0\n\t"
;                 "v_add_f32_dpp %0, %0, %0 quad_perm:[2,3,0,1] row_mask:0xf bank_mask:0xf bound_ctrl:1\n\t"
;                 "v_add_f32_dpp %1, %1, %1 quad_perm:[2,3,0,1] row_mask:0xf bank_mask:0xf bound_ctrl:1\n\t"
;                 "s_nop 0\n\t"
;                 "v_add_f32_dpp %0, %0, %0 row_half_mirror row_mask:0xf bank_mask:0xf bound_ctrl:1\n\t"
;                 "v_add_f32_dpp %1, %1, %1 row_half_mirror row_mask:0xf bank_mask:0xf bound_ctrl:1"
;                 : "+v"(da), "+v"(dy));
;             {
;                 f32x2 t0;
;                 t0 = c[8].xy * v0; t0 = c[6].xy * da + t0; sp[0] = sp[0] * c[4].xy + t0;
;                 t0 = c[8].zw * v0; t0 = c[6].zw * da + t0; sp[1] = sp[1] * c[4].zw + t0;
;                 t0 = c[9].xy * v0; t0 = c[7].xy * da + t0; sp[2] = sp[2] * c[5].xy + t0;
;                 t0 = c[9].zw * v0; t0 = c[7].zw * da + t0; sp[3] = sp[3] * c[5].zw + t0;
;             }
;             ybb[t * 32] = dy + da * bk.x + v0 * bk.y;
	v_pk_mul_f32 v[122:123], v[38:39], v[42:43]
	v_pk_mul_f32 v[124:125], v[38:39], v[50:51]
	v_pk_fma_f32 v[122:123], v[36:37], v[40:41], v[122:123]
	v_pk_fma_f32 v[124:125], v[36:37], v[48:49], v[124:125]
	v_pk_fma_f32 v[122:123], v[32:33], v[44:45], v[122:123]
	v_pk_fma_f32 v[124:125], v[32:33], v[52:53], v[124:125]
	v_pk_fma_f32 v[122:123], v[34:35], v[46:47], v[122:123]
	v_pk_fma_f32 v[124:125], v[34:35], v[54:55], v[124:125]
	v_pk_mul_f32 v[126:127], v[72:73], v[94:95] op_sel_hi:[1,0]
	v_add_f32_e32 v166, v122, v123
	v_add_f32_e32 v168, v124, v125
	v_pk_mul_f32 v[128:129], v[74:75], v[94:95] op_sel_hi:[1,0]
	v_pk_mul_f32 v[130:131], v[76:77], v[94:95] op_sel_hi:[1,0]
	v_add_f32_dpp v166, v166, v166 quad_perm:[1,0,3,2] row_mask:0xf bank_mask:0xf bound_ctrl:1
	v_add_f32_dpp v168, v168, v168 quad_perm:[1,0,3,2] row_mask:0xf bank_mask:0xf bound_ctrl:1
	v_pk_mul_f32 v[132:133], v[78:79], v[94:95] op_sel_hi:[1,0]
	v_pk_fma_f32 v[126:127], v[36:37], v[56:57], v[126:127]
	v_add_f32_dpp v166, v166, v166 quad_perm:[2,3,0,1] row_mask:0xf bank_mask:0xf bound_ctrl:1
	v_add_f32_dpp v168, v168, v168 quad_perm:[2,3,0,1] row_mask:0xf bank_mask:0xf bound_ctrl:1
	v_pk_fma_f32 v[128:129], v[38:39], v[58:59], v[128:129]
	v_pk_fma_f32 v[130:131], v[32:33], v[60:61], v[130:131]
	v_add_f32_dpp v166, v166, v166 row_half_mirror row_mask:0xf bank_mask:0xf bound_ctrl:1
	v_add_f32_dpp v168, v168, v168 row_half_mirror row_mask:0xf bank_mask:0xf bound_ctrl:1
	v_pk_fma_f32 v[132:133], v[34:35], v[62:63], v[132:133]
	v_fma_f32 v136, v166, v108, v168
	v_pk_fma_f32 v[36:37], v[64:65], v[166:167], v[126:127] op_sel_hi:[1,0,1]
	v_pk_fma_f32 v[38:39], v[66:67], v[166:167], v[128:129] op_sel_hi:[1,0,1]
	v_pk_fma_f32 v[32:33], v[68:69], v[166:167], v[130:131] op_sel_hi:[1,0,1]
	v_pk_fma_f32 v[34:35], v[70:71], v[166:167], v[132:133] op_sel_hi:[1,0,1]
	v_fma_f32 v136, v94, v109, v136
	ds_write_b32 v95, v136 offset:1536
	ds_read_b128 v[40:43], v120 offset:17920
	ds_read_b128 v[44:47], v120 offset:17936
	ds_read_b128 v[48:51], v120 offset:18176
	ds_read_b128 v[52:55], v120 offset:18192
	ds_read_b128 v[56:59], v120 offset:18432
	ds_read_b128 v[60:63], v120 offset:18448
	ds_read_b128 v[64:67], v120 offset:18688
	ds_read_b128 v[68:71], v120 offset:18704
	ds_read_b128 v[72:75], v120 offset:18944
	ds_read_b128 v[76:79], v120 offset:18960
	ds_read_b32 v94, v96 offset:24064
	ds_read_b64 v[108:109], v121 offset:24800
	s_waitcnt lgkmcnt(12)
	v_pk_mul_f32 v[122:123], v[38:39], v[192:193]
	v_pk_mul_f32 v[124:125], v[38:39], v[200:201]
	v_pk_fma_f32 v[122:123], v[36:37], v[190:191], v[122:123]
	v_pk_fma_f32 v[124:125], v[36:37], v[198:199], v[124:125]
	v_pk_fma_f32 v[122:123], v[32:33], v[194:195], v[122:123]
	v_pk_fma_f32 v[124:125], v[32:33], v[202:203], v[124:125]
	v_pk_fma_f32 v[122:123], v[34:35], v[196:197], v[122:123]
	v_pk_fma_f32 v[124:125], v[34:35], v[204:205], v[124:125]
	v_pk_mul_f32 v[126:127], v[222:223], v[230:231] op_sel_hi:[1,0]
	v_add_f32_e32 v166, v122, v123
	v_add_f32_e32 v168, v124, v125
	v_pk_mul_f32 v[128:129], v[224:225], v[230:231] op_sel_hi:[1,0]
	v_pk_mul_f32 v[130:131], v[226:227], v[230:231] op_sel_hi:[1,0]
	v_add_f32_dpp v166, v166, v166 quad_perm:[1,0,3,2] row_mask:0xf bank_mask:0xf bound_ctrl:1
	v_add_f32_dpp v168, v168, v168 quad_perm:[1,0,3,2] row_mask:0xf bank_mask:0xf bound_ctrl:1
	v_pk_mul_f32 v[132:133], v[228:229], v[230:231] op_sel_hi:[1,0]
	v_pk_fma_f32 v[126:127], v[36:37], v[206:207], v[126:127]
	v_add_f32_dpp v166, v166, v166 quad_perm:[2,3,0,1] row_mask:0xf bank_mask:0xf bound_ctrl:1
	v_add_f32_dpp v168, v168, v168 quad_perm:[2,3,0,1] row_mask:0xf bank_mask:0xf bound_ctrl:1
	v_pk_fma_f32 v[128:129], v[38:39], v[208:209], v[128:129]
	v_pk_fma_f32 v[130:131], v[32:33], v[210:211], v[130:131]
	v_add_f32_dpp v166, v166, v166 row_half_mirror row_mask:0xf bank_mask:0xf bound_ctrl:1
	v_add_f32_dpp v168, v168, v168 row_half_mirror row_mask:0xf bank_mask:0xf bound_ctrl:1
	v_pk_fma_f32 v[132:133], v[34:35], v[212:213], v[132:133]
	v_fma_f32 v136, v166, v232, v168
	v_pk_fma_f32 v[36:37], v[214:215], v[166:167], v[126:127] op_sel_hi:[1,0,1]
	v_pk_fma_f32 v[38:39], v[216:217], v[166:167], v[128:129] op_sel_hi:[1,0,1]
	v_pk_fma_f32 v[32:33], v[218:219], v[166:167], v[130:131] op_sel_hi:[1,0,1]
	v_pk_fma_f32 v[34:35], v[220:221], v[166:167], v[132:133] op_sel_hi:[1,0,1]
	v_fma_f32 v136, v230, v233, v136
	ds_write_b32 v95, v136 offset:1664
	ds_read_b128 v[190:193], v120 offset:19200
	ds_read_b128 v[194:197], v120 offset:19216
	ds_read_b128 v[198:201], v120 offset:19456
	ds_read_b128 v[202:205], v120 offset:19472
	ds_read_b128 v[206:209], v120 offset:19712
	ds_read_b128 v[210:213], v120 offset:19728
	ds_read_b128 v[214:217], v120 offset:19968
	ds_read_b128 v[218:221], v120 offset:19984
	ds_read_b128 v[222:225], v120 offset:20224
	ds_read_b128 v[226:229], v120 offset:20240
	ds_read_b32 v230, v96 offset:24320
	ds_read_b64 v[232:233], v121 offset:24816
	s_waitcnt lgkmcnt(12)
; DI void scan_item(const __attribute__((address_space(4))) Args& a, LAS unsigned char* lds, int ws_, bool is_prompt, int seq, int h, int half, bool dry = false) {
;     ...
;         for (int t = 0; t < SC_CH; ++t) {
;             f32x4 c[10];
; #pragma unroll
;             for (int q = 0; q < 10; ++q) c[q] = n[q];
;             const float v0 = nv; const f32x2 bk = nbk;
;             SC_LOAD(t + 1)
;             __builtin_amdgcn_sched_barrier(0);
;             f32x2 aA = sp[0] * c[0].xy, aY = sp[0] * c[2].xy;
;             aA = sp[1] * c[0].zw + aA; aY = sp[1] * c[2].zw + aY;
;             aA = sp[2] * c[1].xy + aA; aY = sp[2] * c[3].xy + aY;
;             aA = sp[3] * c[1].zw + aA; aY = sp[3] * c[3].zw + aY;
;             float da = aA.x + aA.y, dy = aY.x + aY.y;
;             asm("s_nop 1\n\t"
;                 "v_add_f32_dpp %0, %0, %0 quad_perm:[1,0,3,2] row_mask:0xf bank_mask:0xf bound_ctrl:1\n\t"
;                 "v_add_f32_dpp %1, %1, %1 quad_perm:[1,0,3,2] row_mask:0xf bank_mask:0xf bound_ctrl:1\n\t"
;                 "s_nop 0\n\t"
;                 "v_add_f32_dpp %0, %0, %0 quad_perm:[2,3,0,1] row_mask:0xf bank_mask:0xf bound_ctrl:1\n\t"
;                 "v_add_f32_dpp %1, %1, %1 quad_perm:[2,3,0,1] row_mask:0xf bank_mask:0xf bound_ctrl:1\n\t"
;                 "s_nop 0\n\t"
;                 "v_add_f32_dpp %0, %0, %0 row_half_mirror row_mask:0xf bank_mask:0xf bound_ctrl:1\n\t"
;                 "v_add_f32_dpp %1, %1, %1 row_half_mirror row_mask:0xf bank_mask:0xf bound_ctrl:1"
;                 : "+v"(da), "+v"(dy));
;             {
;                 f32x2 t0;
;                 t0 = c[8].xy * v0; t0 = c[6].xy * da + t0; sp[0] = sp[0] * c[4].xy + t0;
;                 t0 = c[8].zw * v0; t0 = c[6].zw * da + t0; sp[1] = sp[1] * c[4].zw + t0;
;                 t0 = c[9].xy * v0; t0 = c[7].xy * da + t0; sp[2] = sp[2] * c[5].xy + t0;
;                 t0 = c[9].zw * v0; t0 = c[7].zw * da + t0; sp[3] = sp[3] * c[5].zw + t0;
;             }
;             ybb[t * 32] = dy + da * bk.x + v0 * bk.y;
;         }
;     ...
;     };
;     if (!consumer) { load_raw(0); produce(0, 0); if (NCH > 1) load_raw(1); }
;     __syncthreads();
;     for (int ch = 0; ch < NCH; ++ch) {
;         if (consumer) consume(ch & 1);
;         else {
;             if (ch >= 1) post(ch - 1, (ch - 1) & 1);
	v_pk_mul_f32 v[122:123], v[38:39], v[42:43]
	v_pk_mul_f32 v[124:125], v[38:39], v[50:51]
	v_pk_fma_f32 v[122:123], v[36:37], v[40:41], v[122:123]
	v_pk_fma_f32 v[124:125], v[36:37], v[48:49], v[124:125]
	v_pk_fma_f32 v[122:123], v[32:33], v[44:45], v[122:123]
	v_pk_fma_f32 v[124:125], v[32:33], v[52:53], v[124:125]
	v_pk_fma_f32 v[122:123], v[34:35], v[46:47], v[122:123]
	v_pk_fma_f32 v[124:125], v[34:35], v[54:55], v[124:125]
	v_pk_mul_f32 v[126:127], v[72:73], v[94:95] op_sel_hi:[1,0]
	v_add_f32_e32 v166, v122, v123
	v_add_f32_e32 v168, v124, v125
	v_pk_mul_f32 v[128:129], v[74:75], v[94:95] op_sel_hi:[1,0]
	v_pk_mul_f32 v[130:131], v[76:77], v[94:95] op_sel_hi:[1,0]
	v_add_f32_dpp v166, v166, v166 quad_perm:[1,0,3,2] row_mask:0xf bank_mask:0xf bound_ctrl:1
	v_add_f32_dpp v168, v168, v168 quad_perm:[1,0,3,2] row_mask:0xf bank_mask:0xf bound_ctrl:1
	v_pk_mul_f32 v[132:133], v[78:79], v[94:95] op_sel_hi:[1,0]
	v_pk_fma_f32 v[126:127], v[36:37], v[56:57], v[126:127]
	v_add_f32_dpp v166, v166, v166 quad_perm:[2,3,0,1] row_mask:0xf bank_mask:0xf bound_ctrl:1
	v_add_f32_dpp v168, v168, v168 quad_perm:[2,3,0,1] row_mask:0xf bank_mask:0xf bound_ctrl:1
	v_pk_fma_f32 v[128:129], v[38:39], v[58:59], v[128:129]
	v_pk_fma_f32 v[130:131], v[32:33], v[60:61], v[130:131]
	v_add_f32_dpp v166, v166, v166 row_half_mirror row_mask:0xf bank_mask:0xf bound_ctrl:1
	v_add_f32_dpp v168, v168, v168 row_half_mirror row_mask:0xf bank_mask:0xf bound_ctrl:1
	v_pk_fma_f32 v[132:133], v[34:35], v[62:63], v[132:133]
	v_fma_f32 v136, v166, v108, v168
	v_pk_fma_f32 v[36:37], v[64:65], v[166:167], v[126:127] op_sel_hi:[1,0,1]
	v_pk_fma_f32 v[38:39], v[66:67], v[166:167], v[128:129] op_sel_hi:[1,0,1]
	v_pk_fma_f32 v[32:33], v[68:69], v[166:167], v[130:131] op_sel_hi:[1,0,1]
	v_pk_fma_f32 v[34:35], v[70:71], v[166:167], v[132:133] op_sel_hi:[1,0,1]
	v_fma_f32 v136, v94, v109, v136
	ds_write_b32 v95, v136 offset:1792
	s_waitcnt lgkmcnt(0)
	v_pk_mul_f32 v[122:123], v[38:39], v[192:193]
	v_pk_mul_f32 v[124:125], v[38:39], v[200:201]
	v_pk_fma_f32 v[122:123], v[36:37], v[190:191], v[122:123]
	v_pk_fma_f32 v[124:125], v[36:37], v[198:199], v[124:125]
	v_pk_fma_f32 v[122:123], v[32:33], v[194:195], v[122:123]
	v_pk_fma_f32 v[124:125], v[32:33], v[202:203], v[124:125]
	v_pk_fma_f32 v[122:123], v[34:35], v[196:197], v[122:123]
	v_pk_fma_f32 v[124:125], v[34:35], v[204:205], v[124:125]
	v_pk_mul_f32 v[126:127], v[222:223], v[230:231] op_sel_hi:[1,0]
	v_add_f32_e32 v166, v122, v123
	v_add_f32_e32 v168, v124, v125
	v_pk_mul_f32 v[128:129], v[224:225], v[230:231] op_sel_hi:[1,0]
	v_pk_mul_f32 v[130:131], v[226:227], v[230:231] op_sel_hi:[1,0]
	v_add_f32_dpp v166, v166, v166 quad_perm:[1,0,3,2] row_mask:0xf bank_mask:0xf bound_ctrl:1
	v_add_f32_dpp v168, v168, v168 quad_perm:[1,0,3,2] row_mask:0xf bank_mask:0xf bound_ctrl:1
	v_pk_mul_f32 v[132:133], v[228:229], v[230:231] op_sel_hi:[1,0]
	v_pk_fma_f32 v[126:127], v[36:37], v[206:207], v[126:127]
	v_add_f32_dpp v166, v166, v166 quad_perm:[2,3,0,1] row_mask:0xf bank_mask:0xf bound_ctrl:1
	v_add_f32_dpp v168, v168, v168 quad_perm:[2,3,0,1] row_mask:0xf bank_mask:0xf bound_ctrl:1
	v_pk_fma_f32 v[128:129], v[38:39], v[208:209], v[128:129]
	v_pk_fma_f32 v[130:131], v[32:33], v[210:211], v[130:131]
	v_add_f32_dpp v166, v166, v166 row_half_mirror row_mask:0xf bank_mask:0xf bound_ctrl:1
	v_add_f32_dpp v168, v168, v168 row_half_mirror row_mask:0xf bank_mask:0xf bound_ctrl:1
	v_pk_fma_f32 v[132:133], v[34:35], v[212:213], v[132:133]
	v_fma_f32 v136, v166, v232, v168
	v_pk_fma_f32 v[36:37], v[214:215], v[166:167], v[126:127] op_sel_hi:[1,0,1]
	v_pk_fma_f32 v[38:39], v[216:217], v[166:167], v[128:129] op_sel_hi:[1,0,1]
	v_pk_fma_f32 v[32:33], v[218:219], v[166:167], v[130:131] op_sel_hi:[1,0,1]
	v_pk_fma_f32 v[34:35], v[220:221], v[166:167], v[132:133] op_sel_hi:[1,0,1]
	v_fma_f32 v136, v230, v233, v136
	ds_write_b32 v95, v136 offset:1920
	s_setprio 0
	s_add_i32 s24, s24, 1
	s_branch .LBB0_1524
